# P2 entry: lambda-vector loads issued at the P1 exit, before the team barrier
# speedup vs baseline: 1.0032x; 1.0010x over previous
; __global__ void __launch_bounds__(NWAVES * 64, 2) mega_fwd(Args args) {
;     ...
;         const float d1 = wave_sum(lq1[lane] * lk1[lane]), d2 = wave_sum(lq2[lane] * lk2[lane]);
.LBB0_296:
	s_waitcnt vmcnt(0)
	s_barrier
	v_lshlrev_b32_e32 v253, 2, v194
	global_load_dword v249, v253, s[14:15]
	global_load_dword v250, v253, s[16:17]
	global_load_dword v251, v253, s[18:19]
	global_load_dword v252, v253, s[20:21]

; __global__ void __launch_bounds__(NWAVES * 64, 2) mega_fwd(Args args) {
;     ...
;         const float d1 = wave_sum(lq1[lane] * lk1[lane]), d2 = wave_sum(lq2[lane] * lk2[lane]);
;         const float lam = expf(d1) - expf(d2) + 0.2f;
;         const att::SideJob SJ{w_out, w_up, w_dn, g_mlp, WOUT, WUP, WDN, vcu, 256, (G == 256) ? 36 : 0};
;         for (int u = vcu; u < BATCH * NHEAD * 16; u += G) {
;             const int bh = u >> 4, qb = u & 15;
;             datt::diff_unit2<8>(PROJ, KBI, VBI, out, MIX, subg, lam, bh >> 3, bh & 7, qb, (char*)lds + RING_OFF, SJ, (const unsigned*)(ctl + CW_P1D), (G == 256 && N_LAUNCHES != PER_PHASE) ? 256u : 0u);
.Lp2_diff_entry:
	v_lshlrev_b32_e32 v1, 2, v194
	s_waitcnt vmcnt(0)
	v_mov_b32_e32 v2, v249
	v_mov_b32_e32 v3, v250
	v_mov_b32_e32 v4, v251
	v_mov_b32_e32 v5, v252
	v_mbcnt_lo_u32_b32 v1, -1, 0
	v_mbcnt_hi_u32_b32 v6, -1, v1
	v_and_b32_e32 v1, 64, v6
	v_xor_b32_e32 v7, 1, v6
	s_waitcnt vmcnt(0)
	v_add_u32_e32 v13, 64, v1
	v_cmp_lt_i32_e32 vcc, v7, v13
	v_xor_b32_e32 v8, 2, v6
	v_xor_b32_e32 v9, 4, v6
	v_cndmask_b32_e32 v1, v6, v7, vcc
	v_lshlrev_b32_e32 v1, 2, v1
	v_cmp_lt_i32_e32 vcc, v8, v13
	v_xor_b32_e32 v10, 8, v6
	v_xor_b32_e32 v11, 16, v6
	v_cndmask_b32_e32 v8, v6, v8, vcc
	v_lshlrev_b32_e32 v182, 2, v8
	v_cmp_lt_i32_e32 vcc, v9, v13
	v_xor_b32_e32 v12, 32, v6
	s_cmpk_gt_i32 s76, 0xff
	s_mov_b32 s1, 0
	v_mul_f32_e32 v7, v2, v3
	ds_bpermute_b32 v7, v1, v7
	v_mul_f32_e32 v14, v4, v5
	ds_bpermute_b32 v14, v1, v14
	s_waitcnt lgkmcnt(1)
	v_fmac_f32_e32 v7, v2, v3
	ds_bpermute_b32 v2, v182, v7
	s_waitcnt lgkmcnt(1)
	v_fmac_f32_e32 v14, v4, v5
	ds_bpermute_b32 v3, v182, v14
	v_cndmask_b32_e32 v4, v6, v9, vcc
	v_lshlrev_b32_e32 v183, 2, v4
	s_waitcnt lgkmcnt(1)
	v_add_f32_e32 v2, v7, v2
	ds_bpermute_b32 v4, v183, v2
	s_waitcnt lgkmcnt(1)
	v_add_f32_e32 v3, v14, v3
	ds_bpermute_b32 v5, v183, v3
	v_cmp_lt_i32_e32 vcc, v10, v13
	s_waitcnt lgkmcnt(1)
	v_add_f32_e32 v2, v2, v4
	v_cndmask_b32_e32 v7, v6, v10, vcc
	v_lshlrev_b32_e32 v184, 2, v7
	s_waitcnt lgkmcnt(0)
	v_add_f32_e32 v3, v3, v5
	ds_bpermute_b32 v4, v184, v2
	ds_bpermute_b32 v5, v184, v3
	v_cmp_lt_i32_e32 vcc, v11, v13
	s_waitcnt lgkmcnt(1)
	v_add_f32_e32 v2, v2, v4
	v_cndmask_b32_e32 v7, v6, v11, vcc
	v_lshlrev_b32_e32 v185, 2, v7
	s_waitcnt lgkmcnt(0)
	v_add_f32_e32 v3, v3, v5
	ds_bpermute_b32 v4, v185, v2
	ds_bpermute_b32 v5, v185, v3
	v_cmp_lt_i32_e32 vcc, v12, v13
	s_waitcnt lgkmcnt(1)
	v_add_f32_e32 v4, v2, v4
	v_cndmask_b32_e32 v6, v6, v12, vcc
	v_lshlrev_b32_e32 v6, 2, v6
	s_waitcnt lgkmcnt(0)
	v_add_f32_e32 v2, v3, v5
	ds_bpermute_b32 v5, v6, v4
	ds_bpermute_b32 v3, v6, v2
	s_cbranch_scc1 .LBB0_574
	s_waitcnt lgkmcnt(1)
	v_add_f32_e32 v4, v4, v5
	s_mov_b32 s0, 0x3fb8aa3b
	v_mul_f32_e32 v5, 0x3fb8aa3b, v4
	v_fma_f32 v6, v4, s0, -v5
	v_rndne_f32_e32 v7, v5
	v_fmac_f32_e32 v6, 0x32a5705f, v4
	v_sub_f32_e32 v5, v5, v7
	v_add_f32_e32 v5, v5, v6
	v_exp_f32_e32 v5, v5
	v_cvt_i32_f32_e32 v6, v7
	s_waitcnt lgkmcnt(0)
	v_add_f32_e32 v2, v2, v3
	s_mov_b32 s2, 0xc2ce8ed0
	v_cmp_ngt_f32_e32 vcc, s2, v4
	v_ldexp_f32 v3, v5, v6
	v_mul_f32_e32 v5, 0x3fb8aa3b, v2
	v_fma_f32 v6, v2, s0, -v5
	v_rndne_f32_e32 v7, v5
	v_fmac_f32_e32 v6, 0x32a5705f, v2
	v_sub_f32_e32 v5, v5, v7
	v_add_f32_e32 v5, v5, v6
	v_exp_f32_e32 v5, v5
	v_cvt_i32_f32_e32 v6, v7
	s_mov_b32 s3, 0x42b17218
	v_cndmask_b32_e32 v3, 0, v3, vcc
	v_mov_b32_e32 v7, 0x7f800000
	v_cmp_nlt_f32_e32 vcc, s3, v4
	v_readlane_b32 s6, v242, 12
	v_ldexp_f32 v4, v5, v6
	v_cndmask_b32_e32 v3, v7, v3, vcc
	v_cmp_ngt_f32_e32 vcc, s2, v2
	v_readlane_b32 s7, v242, 13
	v_mov_b32_e32 v147, 0
	v_cndmask_b32_e32 v4, 0, v4, vcc
	v_cmp_nlt_f32_e32 vcc, s3, v2
	s_and_b64 s[2:3], s[6:7], exec
	s_cselect_b32 s3, 36, 0
	s_add_u32 s12, s70, 0xe014100
	s_addc_u32 s13, s71, 0
	s_and_b64 s[4:5], s[6:7], exec
	s_cselect_b32 s42, 0x100, 0
	s_lshl_b32 s0, s76, 6
	s_and_b32 s43, s0, 0x7c0
	v_cndmask_b32_e32 v2, v7, v4, vcc
	s_add_u32 s44, s70, 0x4002000
	v_sub_f32_e32 v2, v3, v2
	s_addc_u32 s45, s71, 0
	v_add_f32_e32 v186, 0x3e4ccccd, v2
	s_add_u32 s46, s70, 0x500c000
	v_cndmask_b32_e64 v2, 0, 1, s[6:7]
	s_addc_u32 s47, s71, 0
	v_cmp_ne_u32_e64 s[4:5], 1, v2
	s_mov_b64 s[14:15], 0x400
	s_mov_b64 s[16:17], 0x4000
	s_add_i32 s48, 0, 0x1c800
	s_mov_b64 s[18:19], 0x8000
	s_mov_b32 s49, 0x41000000
	s_movk_i32 s78, 0x1000
	v_mov_b32_e32 v187, 0x3727c5ac
	s_mov_b32 s79, s76
	s_branch .LBB0_399
